# ST4: out-proj phase start staggered by 8us for the workgroups with XCD-local index >= 32, so co-resident workgroups overlap MFMA k-loop with the other's memory-bound epilogue
# baseline (speedup 1.0000x reference)
.Lfbq_out:
.LBB0_992:
	s_or_b64 exec, exec, s[0:1]
	v_readlane_b32 s4, v232, 14
	s_nop 3
	s_bitcmp1_b32 s4, 10
	s_cbranch_scc0 .Lst_go
	s_memrealtime s[4:5]
	s_waitcnt lgkmcnt(0)
	s_add_u32 s4, s4, 800
	s_addc_u32 s5, s5, 0
.Lst_spin:
	s_sleep 8
	s_memrealtime s[0:1]
	s_waitcnt lgkmcnt(0)
	s_sub_u32 s0, s0, s4
	s_subb_u32 s1, s1, s5
	s_cmp_lt_i32 s1, 0
	s_cbranch_scc1 .Lst_spin
.Lst_go:
	v_mov_b32_e32 v6, v156
	s_waitcnt lgkmcnt(0)
	s_barrier
	s_lshl_b32 s0, s2, 21
	v_readlane_b32 s1, v232, 12
	s_add_u32 s12, s1, s0
	v_and_b32_e32 v0, 31, v6
	v_readlane_b32 s0, v232, 13
	v_lshlrev_b32_e32 v9, 2, v0
	v_ashrrev_i32_e32 v0, 1, v6
	s_addc_u32 s13, s0, 0
	v_readlane_b32 s0, v232, 16
	v_readlane_b32 s48, v234, 2
	v_and_b32_e32 v2, 0xffffffc0, v0
	v_readlane_b32 s1, v232, 17
	v_readlane_b32 s49, v234, 3
	v_ashrrev_i32_e32 v3, 31, v2
	v_lshlrev_b32_e32 v0, 2, v6
	s_and_b64 s[0:1], s[0:1], exec
	s_mov_b64 s[4:5], s[48:49]
	v_lshlrev_b32_e32 v7, 8, v6
	v_lshlrev_b64 v[66:67], 10, v[2:3]
	v_and_b32_e32 v2, 60, v0
	s_cselect_b32 s1, s5, s79
	s_cselect_b32 s0, s4, s78
	v_and_b32_e32 v8, 0xffffc000, v7
	v_lshlrev_b32_e32 v0, 2, v2
	v_lshl_add_u64 v[4:5], s[0:1], 0, v[0:1]
	v_or_b32_e32 v11, v8, v0
	v_lshlrev_b32_e32 v0, 5, v6
	v_bfe_u32 v3, v6, 4, 2
	v_and_b32_e32 v0, 0x400, v0
	v_or3_b32 v125, v8, v9, v0
	v_or_b32_e32 v0, 4, v3
	s_waitcnt vmcnt(1)
	v_lshlrev_b32_e32 v13, 8, v0
	v_lshlrev_b32_e32 v8, 10, v0
	v_or_b32_e32 v0, 8, v3
	v_lshlrev_b32_e32 v15, 8, v0
	v_lshlrev_b32_e32 v10, 10, v0
	v_or_b32_e32 v0, 12, v3
	v_lshlrev_b32_e32 v17, 8, v0
	v_lshlrev_b32_e32 v12, 10, v0
	v_or_b32_e32 v0, 16, v3
	v_lshlrev_b32_e32 v19, 8, v0
	v_lshlrev_b32_e32 v14, 10, v0
	v_or_b32_e32 v0, 20, v3
	v_lshlrev_b32_e32 v21, 8, v0
	v_lshlrev_b32_e32 v16, 10, v0
	v_or_b32_e32 v0, 24, v3
	v_lshlrev_b32_e32 v23, 8, v0
	v_lshlrev_b32_e32 v18, 10, v0
	v_or_b32_e32 v0, 28, v3
	v_lshlrev_b32_e32 v25, 8, v0
	v_lshlrev_b32_e32 v20, 10, v0
	v_or_b32_e32 v0, 32, v3
	v_lshlrev_b32_e32 v27, 8, v0
	v_lshlrev_b32_e32 v22, 10, v0
	v_or_b32_e32 v0, 36, v3
	v_lshlrev_b32_e32 v29, 8, v0
	v_lshlrev_b32_e32 v24, 10, v0
	v_or_b32_e32 v0, 40, v3
	v_lshlrev_b32_e32 v31, 8, v0
	v_lshlrev_b32_e32 v26, 10, v0
	v_or_b32_e32 v0, 44, v3
	v_lshlrev_b32_e32 v33, 8, v0
	v_lshlrev_b32_e32 v28, 10, v0
	v_or_b32_e32 v0, 48, v3
	v_lshlrev_b32_e32 v35, 8, v0
	v_lshlrev_b32_e32 v30, 10, v0
	v_or_b32_e32 v0, 52, v3
	v_lshlrev_b32_e32 v37, 8, v0
	v_lshlrev_b32_e32 v32, 10, v0
	v_or_b32_e32 v0, 56, v3
	v_readlane_b32 s54, v234, 8
	v_readlane_b32 s55, v234, 9
	v_readlane_b32 s56, v234, 10
	v_readlane_b32 s57, v234, 11
	v_readlane_b32 s58, v234, 12
	v_readlane_b32 s59, v234, 13
	v_readlane_b32 s62, v234, 16
	v_readlane_b32 s63, v234, 17
	v_lshlrev_b32_e32 v38, 8, v0
	v_lshlrev_b32_e32 v34, 10, v0
	v_or_b32_e32 v0, 60, v3
	v_readlane_b32 s50, v234, 4
	v_readlane_b32 s51, v234, 5
	v_readlane_b32 s52, v234, 6
	v_readlane_b32 s60, v234, 14
	v_readlane_b32 s61, v234, 15
	v_and_or_b32 v66, v6, 64, v66
	v_lshlrev_b32_e32 v9, 8, v3
	v_lshlrev_b32_e32 v6, 10, v3
	v_lshlrev_b32_e32 v3, 8, v0
	v_lshlrev_b32_e32 v36, 10, v0
	v_and_b32_e32 v0, 0x3000, v7
	v_readlane_b32 s48, v232, 18
	v_readlane_b32 s54, v232, 23
	v_readlane_b32 s58, v232, 25
	v_readlane_b32 s62, v232, 27
	v_readlane_b32 s56, v232, 29
	v_lshl_add_u64 v[68:69], v[4:5], 0, v[0:1]
	s_lshl_b64 s[0:1], s[2:3], 21
	s_mov_b32 s14, 0
	v_add_u32_e32 v144, v11, v9
	v_lshlrev_b32_e32 v70, 2, v6
	v_lshlrev_b32_e32 v72, 2, v2
	v_add_u32_e32 v145, v11, v13
	v_lshlrev_b32_e32 v74, 2, v8
	v_add_u32_e32 v146, v11, v15
	v_lshlrev_b32_e32 v76, 2, v10
	v_add_u32_e32 v147, v11, v17
	v_lshlrev_b32_e32 v78, 2, v12
	v_add_u32_e32 v148, v11, v19
	v_lshlrev_b32_e32 v80, 2, v14
	v_add_u32_e32 v149, v11, v21
	v_lshlrev_b32_e32 v82, 2, v16
	v_add_u32_e32 v150, v11, v23
	v_lshlrev_b32_e32 v84, 2, v18
	v_add_u32_e32 v151, v11, v25
	v_lshlrev_b32_e32 v86, 2, v20
	v_add_u32_e32 v152, v11, v27
	v_lshlrev_b32_e32 v88, 2, v22
	v_add_u32_e32 v153, v11, v29
	v_lshlrev_b32_e32 v90, 2, v24
	v_add_u32_e32 v154, v11, v31
	v_lshlrev_b32_e32 v92, 2, v26
	v_add_u32_e32 v155, v11, v33
	v_lshlrev_b32_e32 v94, 2, v28
	v_add_u32_e32 v180, v11, v35
	v_lshlrev_b32_e32 v96, 2, v30
	v_add_u32_e32 v181, v11, v37
	v_lshlrev_b32_e32 v98, 2, v32
	v_add_u32_e32 v182, v11, v38
	v_lshlrev_b32_e32 v100, 2, v34
	v_add_u32_e32 v183, v11, v3
	v_lshlrev_b32_e32 v102, 2, v36
	v_readlane_b32 s74, v234, 36
	v_readlane_b32 s60, v234, 38
	v_readlane_b32 s49, v232, 19
	v_readlane_b32 s50, v232, 20
	v_readlane_b32 s51, v232, 21
	v_readlane_b32 s52, v232, 22
	v_readlane_b32 s55, v232, 24
	v_readlane_b32 s59, v232, 26
	v_readlane_b32 s63, v232, 28
	v_readlane_b32 s57, v232, 30
	s_movk_i32 s3, 0x4000
	v_readlane_b32 s53, v234, 7
	v_readlane_b32 s75, v234, 37
	v_readlane_b32 s61, v234, 39
	s_branch .LBB0_995
